# diff-attention tile loops: first four K-fragment reads issued right after the tile barrier, scalar DMA-destination set-up in their shadow
# baseline (speedup 1.0000x reference)
.LBB0_291:
	v_add_u32_e32 v0, s2, v199
	ds_read_b128 v[130:133], v0
	ds_read_b128 v[188:191], v0 offset:1024
	ds_read_b128 v[248:251], v0 offset:2048
	ds_read_b128 v[214:217], v0 offset:3072
	s_lshl_b32 s52, s49, 14
	s_add_i32 s52, s4, s52
	s_add_i32 s53, s52, 0x2000
	s_add_i32 s54, s2, 0x4000
	s_cmp_lg_u32 s48, 2
	s_cselect_b32 s54, s54, 0
	s_add_i32 s55, s54, s41
	s_add_i32 s55, s55, 0xc000
	s_add_i32 s54, s54, s42
	s_add_i32 s54, s54, 0xc000
	s_add_i32 s0, s47, -2
	s_waitcnt lgkmcnt(3)
	v_mfma_f32_32x32x16_bf16 v[130:145], v[130:133], v[146:149], 0
	s_waitcnt lgkmcnt(2)
	v_mfma_f32_32x32x16_bf16 v[130:145], v[188:191], v[150:153], v[130:145]
	ds_read_b128 v[188:191], v0 offset:4096
	s_cmp_lt_u32 s47, s44
	s_cbranch_scc0 .Lmy_a_nok1
	s_mov_b32 m0, s52
	s_nop 0
	global_load_lds_dwordx4 v[210:211], off

.LBB0_1615:
	v_add_u32_e32 v0, s2, v199
	ds_read_b128 v[130:133], v0
	ds_read_b128 v[188:191], v0 offset:1024
	ds_read_b128 v[248:251], v0 offset:2048
	ds_read_b128 v[214:217], v0 offset:3072
	s_lshl_b32 s52, s47, 14
	s_add_i32 s52, s4, s52
	s_add_i32 s53, s52, 0x2000
	s_add_i32 s54, s2, 0x4000
	s_cmp_lg_u32 s46, 2
	s_cselect_b32 s54, s54, 0
	s_add_i32 s55, s54, s39
	s_add_i32 s55, s55, 0xc000
	s_add_i32 s54, s54, s40
	s_add_i32 s54, s54, 0xc000
	s_add_i32 s0, s45, -2
	s_waitcnt lgkmcnt(3)
	v_mfma_f32_32x32x16_bf16 v[130:145], v[130:133], v[146:149], 0
	s_waitcnt lgkmcnt(2)
	v_mfma_f32_32x32x16_bf16 v[130:145], v[188:191], v[150:153], v[130:145]
	ds_read_b128 v[188:191], v0 offset:4096
	s_cmp_lt_u32 s45, s42
	s_cbranch_scc0 .Lmy_b_nok1
	s_mov_b32 m0, s52
	s_nop 0
	global_load_lds_dwordx4 v[210:211], off
